# prep unit: completion flag published after the next work-loop drain+barrier instead of a drain+barrier in the unit tail; no drain before the queue fetch atomic (all edits size-preserving / out of line
# speedup vs baseline: 1.0064x; 1.0064x over previous
; __device__ __forceinline__ int fetch_item(unsigned* ctr, unsigned char* lds) {
;     volatile int* slot = (volatile int*)(lds + LDS_SLOT);
;     __syncthreads();
;     if (my_tid() == 0) *slot = (int)atomicAdd(ctr, 1u);
;     __syncthreads();
;     return *slot;
; }
; __device__ void run_phase(const Params& p, unsigned char* lds, int ph) {
;     ...
;             const int it = fetch_item(ctr, lds);
;             if (it >= 3120) break;
;             if (it < 16) { const int bh = it;
;                 fcum_unit(lds, bh, (const float*)(ws + WS_SCAL), p.in[I_FGB] + l * 4, (float*)(ws + WS_F) , (const bf16_t*)(ws + WS_PAB) + (size_t)(bh >> 2) * SEQ * 1536 + 1024 + (bh & 3) * 64, (float*)(ws + WS_KN) + bh * 128, (const bf16_t*)(ws + WS_PAB) + (size_t)(bh >> 2) * SEQ * 1536 + 256 + (bh & 3) * 64, p.in[I_REL] + (size_t)(l * 4 + (bh & 3)) * 320, (float*)(ws + WS_AB) + bh * 2, uflag + 2048 + bh, fval); }
;             else if (it < 48) { const int j = it - 16;
;                 for (int rep = 0; rep < REP_SCAN; ++rep) { scan_unit(lds, j >> 1, j & 1, ws + WS_PREP, (const float*)(ws + WS_EGL), uflag + (j >> 1) * 128, fval); __syncthreads(); } }
;             else if (it < 2096) { const int j = it - 48, n = j >> 4, bh = j & 15, h = bh & 3;
;                 prep_unit(lds, bh, n, (const bf16_t*)(ws + WS_PC), (const float*)(ws + WS_SCAL), p.in[I_CONVW] + (size_t)l * 4 * 1536, p.in[I_ALOG][l * 4 + h], p.in[I_DTB][l * 4 + h],
;                           ws + WS_PREP + (size_t)(bh * 128 + n) * PREP_UNIT, (float*)(ws + WS_EGL), uflag + bh * 128 + n, fval); }
;             else if (it < 2608) { const int j = it - 2096, qb = j & 31, bh = j >> 5, b = bh >> 2, h = bh & 3;
;                 for (int rep = 0; rep < REP_A; ++rep) { attn_unit<1>(lds, b, qb, pab + h * 64, pab + 256 + h * 64, pab + 512 + h * 64, 1536, hbuf + h * 64, DM, nullptr, p.in[I_REL] + (size_t)(l * 4 + h) * 320, (const float*)(ws + WS_AB) + bh * 2, uflag + 2048 + bh, fval); __syncthreads(); } }
;             else { const int j = it - 2608, qb = 31 - (j >> 4), bh = j & 15, b = bh >> 2, h = bh & 3;
;                 for (int rep = 0; rep < REP_FOX; ++rep) { attn_unit<0>(lds, b, qb, pab + 768 + h * 64, pab + 1024 + h * 64, pab + 1280 + h * 64, 1536, hbuf + 256 + h * 64, DM, (const float*)(ws + WS_F) + (size_t)bh * SEQ, nullptr, (const float*)(ws + WS_KN) + bh * 128, uflag + 2048 + bh, fval); __syncthreads(); } }
.LBB0_174:
	v_mov_b32_e32 v0, v212
	s_waitcnt lgkmcnt(0)
	s_barrier
	s_nop 0
	v_cmp_eq_u32_e32 vcc, 0, v0
	s_and_saveexec_b64 s[0:1], vcc
	s_cbranch_execz .LBB0_176
	v_readlane_b32 s4, v255, 7
	v_readlane_b32 s5, v255, 8
	s_mov_b64 s[2:3], src_shared_base
	s_add_i32 s2, 0, 0x26400
	s_nop 0
	v_mov_b64_e32 v[2:3], s[4:5]
	global_atomic_add v0, v[2:3], v214, off offset:32 sc0
	s_cmp_lg_u32 s2, -1
	s_cselect_b32 s2, s2, 0
	s_cselect_b32 s3, s3, 0
	v_mov_b32_e32 v2, s2
	v_mov_b32_e32 v3, s3
	s_waitcnt vmcnt(0) lgkmcnt(0)
	ds_write_b32 v2, v0
	s_waitcnt vmcnt(0)
.LBB0_176:
	s_or_b64 exec, exec, s[0:1]
	s_mov_b64 s[0:1], src_shared_base
	s_add_i32 s0, 0, 0x26400
	s_cmp_lg_u32 s0, -1
	s_cselect_b32 s0, s0, 0
	s_cselect_b32 s1, s1, 0
	s_waitcnt vmcnt(0)
	v_mov_b32_e32 v2, s0
	v_mov_b32_e32 v3, s1
	s_waitcnt lgkmcnt(0)
	s_barrier
	s_branch .Ldp_s3
	s_nop 0
.Ldp_back3:
	s_nop 0
	s_movk_i32 s0, 0xc30
	s_waitcnt lgkmcnt(0)
	v_add_u32_e32 v2, 32, v90
	v_subrev_u32_e32 v3, 560, v90
	v_cmp_gt_u32_e32 vcc, 576, v90
	s_nop 1
	v_cndmask_b32_e32 v3, v3, v2, vcc
	v_add_u32_e32 v2, -16, v90
	v_cmp_gt_u32_e32 vcc, 592, v2
	s_nop 1
	v_cndmask_b32_e32 v90, v90, v3, vcc
	s_nop 1
	v_cmp_gt_i32_e32 vcc, s0, v90
	s_mov_b64 s[0:1], -1
	s_and_saveexec_b64 s[30:31], vcc
	s_cbranch_execz .LBB0_173
	v_cmp_lt_i32_e32 vcc, 15, v90
	s_and_saveexec_b64 s[0:1], vcc
	s_xor_b64 s[4:5], exec, s[0:1]
	s_cbranch_execz .LBB0_620
	s_mov_b64 s[56:57], s[4:5]
	v_cmp_lt_u32_e32 vcc, 47, v90
	s_and_saveexec_b64 s[0:1], vcc
	s_xor_b64 s[4:5], exec, s[0:1]
	s_cbranch_execz .LBB0_450
	v_writelane_b32 v255, s4, 45
	s_movk_i32 s0, 0x82f
	v_cmp_lt_u32_e32 vcc, s0, v90
	v_writelane_b32 v255, s5, 46
	s_and_saveexec_b64 s[0:1], vcc
	s_xor_b64 s[0:1], exec, s[0:1]
	s_cbranch_execz .LBB0_302
	v_writelane_b32 v255, s0, 47
	s_nop 1
	v_writelane_b32 v255, s1, 48
	s_movk_i32 s0, 0xa2f
	v_cmp_lt_u32_e32 vcc, s0, v90
	s_and_saveexec_b64 s[0:1], vcc
	s_xor_b64 s[0:1], exec, s[0:1]
	v_writelane_b32 v255, s0, 49
	s_nop 1
	v_writelane_b32 v255, s1, 50
	s_cbranch_execz .LBB0_257
	v_and_b32_e32 v6, 15, v90
	v_mov_b32_e32 v146, v212
	s_mov_b64 s[0:1], exec
	v_readlane_b32 s2, v254, 1
	v_readlane_b32 s3, v254, 2
	s_and_b64 s[2:3], s[0:1], s[2:3]
	s_mov_b64 exec, s[2:3]
	s_cbranch_execz .LBB0_186
	v_readlane_b32 s2, v255, 27
	v_lshlrev_b32_e32 v0, 2, v6
	v_readlane_b32 s3, v255, 28
	s_nop 1
	v_lshl_add_u64 v[2:3], s[2:3], 0, v[0:1]
	global_load_dword v0, v[2:3], off sc1
	s_waitcnt vmcnt(0) lgkmcnt(0)
	v_cmp_gt_u32_e32 vcc, s73, v0
	s_and_saveexec_b64 s[2:3], vcc
	s_cbranch_execz .LBB0_185
	s_mov_b64 s[4:5], 0

; __device__ __forceinline__ void handoff_publish_wt(unsigned* flag, unsigned val) {
;     asm volatile("s_waitcnt vmcnt(0)" ::: "memory");
;     __syncthreads();
;     if (threadIdx.x == 0) __hip_atomic_store(flag, val, __ATOMIC_RELAXED, __HIP_MEMORY_SCOPE_AGENT);
; }
; __device__ void prep_unit(unsigned char* lds, int bh, int n, const bf16_t* pc, const float* scal, const float* convw  , float alog, float dtb, unsigned char* unit, float* egl, unsigned* flag, unsigned fval) {
;     ...
;     for (int it = 0; it < 2; ++it) { const int q = tid + NTHR * it; __builtin_amdgcn_raw_buffer_store_b128(*(const u32x4*)((const unsigned char*)stage + q * 16), ur, q * 16, 0, 16); }
;     handoff_publish_wt(flag, fval);
.LBB0_445:
	v_readfirstlane_b32 s8, v94
	v_readfirstlane_b32 s9, v95
	v_readfirstlane_b32 s10, v174
	v_readfirstlane_b32 s11, v175
	v_cmp_eq_u64_e32 vcc, s[8:9], v[94:95]
	s_nop 0
	v_cmp_eq_u64_e64 s[0:1], s[10:11], v[174:175]
	s_and_b64 s[0:1], vcc, s[0:1]
	s_and_saveexec_b64 s[0:1], s[0:1]
	s_waitcnt lgkmcnt(0)
	buffer_store_dwordx4 v[2:5], v6, s[8:11], 0 offen sc1
	s_xor_b64 exec, exec, s[0:1]
	s_cbranch_execnz .LBB0_445
	s_mov_b64 exec, s[2:3]
	v_writelane_b32 v255, 1, 60
	s_mov_b64 s[0:1], exec
	v_readlane_b32 s2, v254, 1
	v_readlane_b32 s3, v254, 2
	s_and_b64 s[2:3], s[0:1], s[2:3]
	v_readlane_b32 s4, v255, 45
	s_xor_b64 s[0:1], s[2:3], s[0:1]
	v_readlane_b32 s5, v255, 46
	s_mov_b64 exec, s[2:3]
	s_cbranch_execz .LBB0_448
	v_readlane_b32 s2, v255, 11
	v_lshlrev_b32_e32 v2, 2, v109
	v_mov_b32_e32 v3, v1
	v_readlane_b32 s3, v255, 12
	v_lshlrev_b32_e32 v0, 2, v0
	s_nop 0
	v_lshl_add_u64 v[2:3], s[2:3], 0, v[2:3]
	v_lshl_add_u64 v[2:3], v[2:3], 0, v[0:1]
	v_mov_b32_e32 v250, v2
	v_mov_b32_e32 v251, v3

; __device__ __forceinline__ int my_tid() { int t = (int)threadIdx.x; asm volatile("" : "+v"(t)); return t; }
; __device__ __forceinline__ void handoff_publish_wt(unsigned* flag, unsigned val) {
;     asm volatile("s_waitcnt vmcnt(0)" ::: "memory");
;     __syncthreads();
;     if (threadIdx.x == 0) __hip_atomic_store(flag, val, __ATOMIC_RELAXED, __HIP_MEMORY_SCOPE_AGENT);
; }
; __device__ __forceinline__ int fetch_item(unsigned* ctr, unsigned char* lds) {
;     ...
;     if (my_tid() == 0) *slot = (int)atomicAdd(ctr, 1u);
;     __syncthreads();
;     return *slot;
.Ldp_s1:
	v_writelane_b32 v255, 0, 60
	s_branch .LBB0_174
.Ldp_s3:
	v_readlane_b32 s4, v255, 60
	v_readlane_b32 s2, v254, 1
	v_readlane_b32 s3, v254, 2
	s_cmp_eq_u32 s4, 0
	s_cbranch_scc1 .Ldp_none
	s_mov_b64 s[0:1], exec
	s_and_b64 exec, exec, s[2:3]
	s_cbranch_execz .Ldp_rest
	global_store_dword v[250:251], v226, off sc1
.Ldp_rest:
	s_mov_b64 exec, s[0:1]
	v_writelane_b32 v255, 0, 60
.Ldp_none:
	ds_read_b32 v90, v2
	s_branch .Ldp_back3
